# mixer queue order: next-layer weight-copy units first (no gate needed, fill the wait for gate 0), then FoX long-first
# speedup vs baseline: 1.0081x; 1.0081x over previous
.LBB0_36:
	s_or_b64 exec, exec, s[10:11]
	s_mov_b64 s[10:11], src_shared_base
	s_xor_b64 s[40:41], s[66:67], -1
	s_xor_b64 s[44:45], s[20:21], -1
	s_add_i32 s10, 0, 0x20200
	s_cmp_lg_u32 s10, -1
	s_cselect_b32 s10, s10, 0
	s_cselect_b32 s11, s11, 0
	v_mov_b32_e32 v2, s10
	s_waitcnt lgkmcnt(0)
	v_mov_b32_e32 v3, s11
	s_waitcnt lgkmcnt(0)
	s_barrier
	flat_load_dword v0, v[2:3] sc0 sc1
	s_waitcnt vmcnt(0)
	s_mov_b64 s[38:39], -1
	s_waitcnt lgkmcnt(0)
	v_cmp_gt_i32_e32 vcc, s69, v0
	s_and_saveexec_b64 s[10:11], vcc
	s_cbranch_execz .LBB0_31
	s_cmpk_eq_i32 s69, 0x340
	s_cselect_b32 s18, 0x48, 0
	v_cmp_le_u32_e32 vcc, 0, v0
	v_mov_b32_e32 v2, s18
	s_nop 0
	v_cndmask_b32_e32 v2, 0, v2, vcc
	v_add_u32_e32 v0, v0, v2
	v_mov_b32_e32 v2, 0xffffff78
	v_mov_b32_e32 v3, 0xfffffff8
	v_cmp_gt_u32_e32 vcc, 0x348, v0
	s_nop 1
	v_cndmask_b32_e32 v2, v2, v3, vcc
	v_mov_b32_e32 v3, 0xffffffb8
	v_cmp_gt_u32_e32 vcc, 0x308, v0
	s_nop 1
	v_cndmask_b32_e32 v2, v2, v3, vcc
	v_mov_b32_e32 v3, 0xffffffb8
	v_cmp_gt_u32_e32 vcc, 0x2a8, v0
	s_nop 1
	v_cndmask_b32_e32 v2, v2, v3, vcc
	v_mov_b32_e32 v3, 0xffffffb8
	v_cmp_gt_u32_e32 vcc, 0x1a8, v0
	s_nop 1
	v_cndmask_b32_e32 v2, v2, v3, vcc
	v_mov_b32_e32 v3, 0xffffffb8
	v_cmp_gt_u32_e32 vcc, 0x148, v0
	s_nop 1
	v_cndmask_b32_e32 v2, v2, v3, vcc
	v_mov_b32_e32 v3, 0x340
	v_cmp_gt_u32_e32 vcc, 0x48, v0
	s_nop 1
	v_cndmask_b32_e32 v2, v2, v3, vcc
	v_add_u32_e32 v0, v0, v2
	s_movk_i32 s18, 0x340
	v_cmp_gt_i32_e32 vcc, s18, v0
	s_and_saveexec_b64 s[38:39], vcc
	s_xor_b64 s[38:39], exec, s[38:39]
	v_writelane_b32 v250, s38, 35
	s_nop 1
	v_writelane_b32 v250, s39, 36
	s_cbranch_execz .LBB0_259
	s_movk_i32 s18, 0x260
	v_add_u32_e32 v2, 0xfffffea0, v0
	v_cmp_gt_i32_e32 vcc, s18, v0
	s_movk_i32 s18, 0x1a0
	s_mov_b64 s[42:43], 0
	v_cndmask_b32_e32 v3, v218, v219, vcc
	v_cmp_gt_u32_e32 vcc, s18, v2
	s_movk_i32 s18, 0x1ff
	s_nop 0
	v_cndmask_b32_e32 v2, 0, v3, vcc
	v_add_u32_e32 v2, v2, v0
	v_cmp_lt_i32_e64 s[38:39], s18, v2
	s_and_saveexec_b64 s[18:19], s[38:39]
	s_xor_b64 s[18:19], exec, s[18:19]
	s_cbranch_execz .LBB0_57
	s_and_saveexec_b64 s[24:25], s[44:45]
	s_cbranch_execz .LBB0_56
	s_and_saveexec_b64 s[42:43], s[36:37]
	s_cbranch_execz .LBB0_55
	v_readlane_b32 s44, v252, 2
	v_readlane_b32 s45, v252, 3
	s_load_dword s34, s[44:45], 0x10
	s_load_dword s46, s[44:45], 0x0
	s_waitcnt lgkmcnt(0)
	s_lshr_b32 s34, s34, 16
	s_cmp_lg_u32 s34, 0
	s_cselect_b64 s[44:45], -1, 0
	s_cmp_lg_u64 s[44:45], 0
	s_addc_u32 s34, s46, 0
	s_mov_b32 s46, 0x1000000
	s_branch .LBB0_44
